# prep_c: the head's conv taps are staged into LDS only for the first of the four chunks a half-block prepares (all four share the head), instead of reloading them per chunk
# speedup vs baseline: 1.0098x; 1.0098x over previous
; DI void phase_prep_c(int wv_, int vb_, int nvb_, char* ws_, const Ctx& p, char* smem, int half) {
;     ...
;   for (int k_ = 0; k_ < (2048 + nvb_ - 1) / nvb_; ++k_) {
;     const int uix = (vb_ + k_ * nvb_ < 2048) ? vb_ + k_ * nvb_ : 2047;
;     const int nc = uix & 31, hd = (uix >> 5) & 7, b = uix >> 8;
;     const int n = half * 32 + nc;
;     {
;       const int tid = tidx(wv_);
;       for (int i = tid; i < 1536; i += 256) scw[i] = p.c_conv_w[(i / 384) * 3072 + ((i % 384) >> 7) * 1024 + hd * 128 + (i & 127)];
;       __syncthreads();
.LBB0_243:
	s_mul_i32 s0, s68, s2
	v_readlane_b32 s2, v254, 14
	s_add_i32 s0, s0, s2
	s_min_i32 s12, s0, 0x7ff
	s_mov_b32 s0, s33
	v_mov_b32_e32 v4, v204
	v_readlane_b32 s3, v254, 15
	v_lshl_or_b32 v2, s0, 6, v4
	s_movk_i32 s0, 0x600
	s_bfe_u32 s13, s12, 0x30005
	v_cmp_gt_i32_e32 vcc, s0, v2
	s_cmp_eq_u32 s68, 0
	s_cselect_b64 vcc, vcc, 0
	s_and_saveexec_b64 s[2:3], vcc
	s_cbranch_execz .LBB0_253
	v_max_i32_e32 v0, 0x500, v2
	v_sub_u32_e32 v0, v0, v2
	v_add_u32_e32 v6, 0xff, v0
	s_lshl_b32 s0, s13, 7
	v_and_b32_e32 v5, 0x7f, v2
	v_cmp_lt_u32_e32 vcc, s22, v6
	s_mov_b64 s[18:19], 0
	s_and_saveexec_b64 s[14:15], vcc
	s_xor_b64 s[14:15], exec, s[14:15]
	s_cbranch_execz .LBB0_248
	v_lshrrev_b32_e32 v0, 8, v6
	v_add_u32_e32 v8, 1, v0
	v_and_b32_e32 v9, 0x1fffffe, v8
	v_add_u32_e32 v3, 0x100, v2
	v_or_b32_e32 v0, s0, v5
	v_readlane_b32 s60, v254, 22
	v_mov_b32_e32 v5, v0
	v_lshl_add_u32 v10, v2, 2, v95
	v_mov_b32_e32 v11, v9
	v_mov_b64_e32 v[6:7], v[2:3]
	v_readlane_b32 s61, v254, 23
	v_readlane_b32 s62, v254, 24
	v_readlane_b32 s63, v254, 25
	v_readlane_b32 s64, v254, 26
	v_readlane_b32 s65, v254, 27
	v_readlane_b32 s66, v254, 28
	v_readlane_b32 s67, v254, 29

; #define PG8_LAS __attribute__((address_space(3)))
; __global__ void __launch_bounds__(512, 2) mega(Params pp) {
;     ...
;     switch (op) {
;       case OP_CONVERT: phase_convert(wv_, vb_, nvb_, ws_, p, smem); break;
;       case OP_NORM_MIX: phase_norm(wv_, vb_, nvb_, xcur, p.norm_mix + l * DM, H); break;
;       case OP_GEMM_IN:
;         if (kind == 0) { pg8::EpiB16HN E; E.O = Pm; E.ldc = 4608; E.ncols_norm = 3072; E.nq_cols = 1536; E.gq = p.a_q_gain + j * 64; E.gk = p.a_k_gain + j * 64; E.T = (PG8_LAS float*)(smem0 + 131072);
;           run_gemm(wv8_, H, WT + (size_t)j * 4718592u, 4608, 1024, -1, E); }
;         else if (kind == 1) { pg8::EpiB16HN E; E.O = Pm; E.ldc = 2304; E.ncols_norm = 1280; E.nq_cols = 1024; E.gq = p.b_q_gain; E.gk = p.b_k_gain; E.T = (PG8_LAS float*)(smem0 + 131072);
;           run_gemm(wv8_, H, WT + wOff(4), 2304, 1024, -1, E); }
;         else { pg8::EpiCIn E; E.Q = (u16*)(ws_ + WS_CQKV); E.G = (u16*)(ws_ + WS_CG); E.S = (float*)(ws_ + WS_SIDE); E.half = half;
;           run_gemm(wv8_, H, WT + wOff(6), 4352, 1024, half, E); }
;         break;
;       case OP_HEADNORM:
;         if (kind == 0) phase_headnorm(wv_, vb_, nvb_, Pm, 4608, 48, 24, p.a_q_gain + j * 64, p.a_k_gain + j * 64);
;         else phase_headnorm(wv_, vb_, nvb_, Pm, 2304, 20, 16, p.b_q_gain, p.b_k_gain);
;         break;
;       case OP_ATTN_A: phase_attn_a(wv_, vb_, nvb_, ws_, p, smem); break;
;       case OP_COMBINE_A: phase_combine_a(wv_, vb_, nvb_, ws_, p); break;
;       case OP_GEMM_OUT:
;       case OP_GEMM_W2: {
;         pg8::EpiResid E; E.C = p.out; E.X = xcur;
;         const u16* Ag = H; int Kg = 1024; unsigned wo = wOff(7);
;         if (op == OP_GEMM_W2) { Ag = Pm; Kg = 4096; wo = wOff(12) + (unsigned)l * 4194304u; }
;         else if (kind == 0) { Kg = 512; wo = wOff(2) + (unsigned)j * 524288u; }
;         else if (kind == 1) { wo = wOff(5); }
;         run_gemm(wv8_, Ag, WT + wo, 1024, Kg, -1, E);
;         break; }
;       case OP_MIX_B: if (half == 0) phase_mix_b(wv_, vb_, nvb_, ws_, p, smem); else phase_mix_b2(wv_, vb_, nvb_, ws_, p, smem); break;
;       case OP_PREP_C: phase_prep_c(wv_, vb_, nvb_, ws_, p, smem, half); break;
;       case OP_SCAN_C: phase_scan_c(wv_, vb_, nvb_, ws_, p, smem, half); break;
;       case OP_SCAN_GEMM:
;         if ((int)blockIdx.x < 64) phase_scan_c(wv_, vb_, nvb_, ws_, p, smem, 0);
.LBB0_447:
	s_nop 0
	s_nop 0
	s_nop 0
	s_nop 0
	s_nop 0
	s_nop 0
	s_nop 0
	s_nop 0
	s_nop 0
	s_nop 0
	s_nop 0
	s_nop 0
	s_nop 0
	s_nop 0
	s_mov_b64 s[2:3], 0
